# K/V projection k-loop rewritten: ring of 8 slots, waves 0-3 issue all LDS-DMA 8 tiles ahead, rolling fragment reads, peeled tail
# speedup vs baseline: 1.1746x; 1.0039x over previous
; DI int opaque_tid() { int t = threadIdx.x; asm volatile("" : "+v"(t)); return t; }
;     constexpr int WM = BM / WR, WN = BN / WC, MT = WM / 16, NT = WN / 16, ROWS = BM + BN, NCH = ROWS * 4, NIT = (NCH + 511) / 512, BUF = ROWS * 64, KT = 32;
;     constexpr int NTS = NT / NSEG, D = NST - 1;
;     static_assert(D == 1 || (NCH % 512 == 0), "deep ring needs a uniform per-thread load count");
;     const int tid = opaque_tid(), lane = tid & 63, wid = tid >> 6, wr = wid / WC, wc = wid % WC, l15 = lane & 15, quad = lane >> 4;
;     const int lrow = tid >> 2, lc = tid & 3;
;     const int lcg = lc ^ ((0 - (tid >> 4)) & 3);
;     const int rsw = (quad ^ ((0 - (l15 >> 2)) & 3)) << 4;
; #pragma unroll
;     for (int mt = 0; mt < MT; ++mt)
; #pragma unroll
;         for (int nt = 0; nt < NT; ++nt) acc[mt][nt] = (f32x4){0.f, 0.f, 0.f, 0.f};
;     const unsigned loff = (unsigned)(lrow * 64 + lcg * 16);
;     const int koff = (int)((blockIdx.x >> 3) + (blockIdx.x & 7) * 4) & (KT - 1);
;     auto issue_one = [&](int kt, int b, int i) {
;         const int row = lrow + 128 * i;
;         if ((NCH % 512 == 0) || (i < NCH / 512) || row < ROWS) {
;             const int kq = (kt + koff) & (KT - 1);
;             const char* ua = (const char*)A + (size_t)((DBG & 1) ? 0 : kq) * (BM * 64);
;             const char* ub = (const char*)Bt + (size_t)((DBG & 2) ? 0 : kq) * ((size_t)ldbk * 2);
;             const char* src;
;             if (BM % 128 == 0) src = (i < BM / 128) ? (ua + i * 8192 + loff) : (ub + (i * 128 - BM) * 64 + loff);
;             else if (i == 0) src = (lrow < BM) ? (ua + loff) : (ub + loff - BM * 64);
;             else src = ub + (i * 128 - BM) * 64 + loff;
;             __builtin_amdgcn_global_load_lds((const unsigned*)src, (unsigned*)(lds + b * BUF + i * 8192 + tid * 16), 16, 0, 0);
;         }
;     };
;     auto issue = [&](int kt, int b) {
; #pragma unroll
;         for (int i = 0; i < NIT; ++i) issue_one(kt, b, i);
;     };
;     ...
;     __syncthreads();
; #pragma unroll
;     for (int d = 0; d < D; ++d) issue(d, d);
;     int cb = 0, ib = D;
.LBB0_859:
	s_andn2_b64 vcc, exec, s[6:7]
	s_cbranch_vccnz .LBB0_891
	s_bfe_u32 s0, s2, 0x50002
	s_lshr_b32 s1, s3, 7
	s_and_b32 s3, s2, 3
	s_lshl_b32 s6, s0, 18
	v_readlane_b32 s7, v244, 38
	v_mov_b32_e32 v44, v212
	s_add_u32 s8, s7, s6
	v_readlane_b32 s6, v244, 39
	v_mov_b32_e32 v4, v212
	s_addc_u32 s9, s6, 0
	s_lshl_b32 s6, s1, 20
	v_readlane_b32 s7, v243, 18
	s_add_u32 s7, s7, s6
	v_lshrrev_b32_e32 v0, 4, v4
	v_readlane_b32 s10, v243, 19
	v_sub_u32_e32 v0, 0, v0
	s_addc_u32 s11, s10, 0
	s_lshl_b32 s10, s3, 13
	v_xor_b32_e32 v0, v4, v0
	v_lshlrev_b32_e32 v5, 4, v4
	s_add_u32 s10, s7, s10
	v_and_b32_e32 v2, 0xffffffc0, v5
	v_lshlrev_b32_e32 v0, 4, v0
	s_addc_u32 s11, s11, 0
	v_and_or_b32 v0, v0, 48, v2
	v_lshl_add_u64 v[34:35], s[8:9], 0, v[0:1]
	v_lshl_add_u64 v[36:37], s[10:11], 0, v[0:1]
	v_readlane_b32 s8, v243, 25
	v_add_u32_e32 v0, 0, v5
	v_readlane_b32 s9, v243, 26
	v_readfirstlane_b32 s7, v0
	v_add_u32_e32 v5, 0x2000, v0
	v_lshl_add_u64 v[2:3], v[34:35], 0, s[8:9]
	s_mov_b32 m0, s7
	v_readfirstlane_b32 s7, v5
	v_readlane_b32 s8, v243, 5
	s_waitcnt lgkmcnt(0)
	s_barrier
	global_load_lds_dwordx4 v[2:3], off
	v_lshl_add_u64 v[2:3], v[36:37], 0, s[74:75]
	s_mov_b32 m0, s7
	v_readlane_b32 s9, v243, 6
	v_add_u32_e32 v5, 0x4000, v0
	global_load_lds_dwordx4 v[2:3], off
	v_lshl_add_u64 v[2:3], v[34:35], 0, s[8:9]
	v_readfirstlane_b32 s7, v5
	v_readlane_b32 s8, v243, 20
	v_add_u32_e32 v5, 0x6000, v0
	s_mov_b32 m0, s7
	v_readlane_b32 s9, v243, 21
	v_readfirstlane_b32 s7, v5
	global_load_lds_dwordx4 v[2:3], off
	v_lshl_add_u64 v[2:3], v[36:37], 0, s[8:9]
	s_mov_b32 m0, s7
	v_lshlrev_b32_e32 v5, 2, v4
	global_load_lds_dwordx4 v[2:3], off
	v_ashrrev_i32_e32 v2, 6, v4
	v_lshrrev_b32_e32 v3, 30, v2
	v_add_u32_e32 v3, v2, v3
	v_and_b32_e32 v5, 48, v5
	v_ashrrev_i32_e32 v3, 2, v3
	v_sub_u32_e32 v5, 0, v5
	v_mul_i32_i24_e32 v6, 4, v3
	v_bitop3_b32 v5, v4, 48, v5 bitop3:0x48
	v_lshlrev_b32_e32 v4, 6, v4
	v_sub_u32_e32 v2, v2, v6
	v_and_b32_e32 v4, 0x3c0, v4
	v_lshl_or_b32 v40, v2, 11, v4
	v_mov_b32_e32 v2, 0
	s_mov_b32 s9, 2
	s_mov_b32 s7, 0
	v_add_u32_e32 v38, 0, v5
	v_lshl_or_b32 v39, v3, 12, v4
	v_readlane_b32 s8, v243, 27
	s_mov_b32 s10, 0
	v_mov_b32_e32 v3, v2
	v_mov_b32_e32 v4, v2
	v_mov_b32_e32 v5, v2
	v_mov_b32_e32 v6, v2
	v_mov_b32_e32 v7, v2
	v_mov_b32_e32 v8, v2
	v_mov_b32_e32 v9, v2
	v_mov_b32_e32 v10, v2
	v_mov_b32_e32 v11, v2
	v_mov_b32_e32 v12, v2
	v_mov_b32_e32 v13, v2
	v_mov_b32_e32 v14, v2
	v_mov_b32_e32 v15, v2
	v_mov_b32_e32 v16, v2
	v_mov_b32_e32 v17, v2
	v_mov_b32_e32 v18, v2
	v_mov_b32_e32 v19, v2
	v_mov_b32_e32 v20, v2
	v_mov_b32_e32 v21, v2
	v_mov_b32_e32 v22, v2
	v_mov_b32_e32 v23, v2
	v_mov_b32_e32 v24, v2
	v_mov_b32_e32 v25, v2
	v_mov_b32_e32 v26, v2
	v_mov_b32_e32 v27, v2
	v_mov_b32_e32 v28, v2
	v_mov_b32_e32 v29, v2
	v_mov_b32_e32 v30, v2
	v_mov_b32_e32 v31, v2
	v_mov_b32_e32 v32, v2
	v_mov_b32_e32 v33, v2
	v_readfirstlane_b32 s90, v212
	s_nop 3
	s_cmp_lt_u32 s90, 0x100
	s_cbranch_scc0 .Lpkv_c_entry
	v_readfirstlane_b32 s94, v34
	v_readfirstlane_b32 s95, v35
	v_readfirstlane_b32 s92, v36
	v_readfirstlane_b32 s93, v37
	s_nop 3
	s_lshl_b32 s8, s90, 5
	s_lshl_b32 s40, s90, 4
	v_subrev_u32_e32 v227, s94, v34
	v_add_u32_e32 v227, s8, v227
	s_sub_u32 vcc_lo, s94, s40
	s_subb_u32 vcc_hi, s95, 0
	s_sub_u32 s92, s92, s40
	s_subb_u32 s93, s93, 0
	s_mov_b32 s7, 4
	s_mov_b32 s9, 2
	s_lshl_b32 s94, s9, 14
	s_add_u32 s94, s94, s8
	s_mov_b32 m0, s94
	s_add_i32 s40, s59, s7
	s_and_b32 s40, s40, 62
	s_lshl_b32 s94, s40, 12
	s_add_u32 s94, vcc_lo, s94
	s_addc_u32 s95, vcc_hi, 0
	s_lshl_b32 s40, s40, 14
	global_load_lds_dwordx4 v227, s[94:95]
	global_load_lds_dwordx4 v227, s[94:95] offset:1024
	s_add_u32 s94, s92, s40
	s_addc_u32 s95, s93, 0
	s_add_u32 m0, m0, 0x2000
	s_nop 0
	global_load_lds_dwordx4 v227, s[94:95]
	global_load_lds_dwordx4 v227, s[94:95] offset:1024
	s_mov_b32 s7, 6
	s_mov_b32 s9, 3
	s_lshl_b32 s94, s9, 14
	s_add_u32 s94, s94, s8
	s_mov_b32 m0, s94
	s_add_i32 s40, s59, s7
	s_and_b32 s40, s40, 62
	s_lshl_b32 s94, s40, 12
	s_add_u32 s94, vcc_lo, s94
	s_addc_u32 s95, vcc_hi, 0
	s_lshl_b32 s40, s40, 14
	global_load_lds_dwordx4 v227, s[94:95]
	global_load_lds_dwordx4 v227, s[94:95] offset:1024
	s_add_u32 s94, s92, s40
	s_addc_u32 s95, s93, 0
	s_add_u32 m0, m0, 0x2000
	s_nop 0
	global_load_lds_dwordx4 v227, s[94:95]
	global_load_lds_dwordx4 v227, s[94:95] offset:1024
	s_mov_b32 s7, 8
	s_mov_b32 s9, 4
	s_lshl_b32 s94, s9, 14
	s_add_u32 s94, s94, s8
	s_mov_b32 m0, s94
	s_add_i32 s40, s59, s7
	s_and_b32 s40, s40, 62
	s_lshl_b32 s94, s40, 12
	s_add_u32 s94, vcc_lo, s94
	s_addc_u32 s95, vcc_hi, 0
	s_lshl_b32 s40, s40, 14
	global_load_lds_dwordx4 v227, s[94:95]
	global_load_lds_dwordx4 v227, s[94:95] offset:1024
	s_add_u32 s94, s92, s40
	s_addc_u32 s95, s93, 0
	s_add_u32 m0, m0, 0x2000
	s_nop 0
	global_load_lds_dwordx4 v227, s[94:95]
	global_load_lds_dwordx4 v227, s[94:95] offset:1024
	s_mov_b32 s7, 10
	s_mov_b32 s9, 5
	s_lshl_b32 s94, s9, 14
	s_add_u32 s94, s94, s8
	s_mov_b32 m0, s94
	s_add_i32 s40, s59, s7
	s_and_b32 s40, s40, 62
	s_lshl_b32 s94, s40, 12
	s_add_u32 s94, vcc_lo, s94
	s_addc_u32 s95, vcc_hi, 0
	s_lshl_b32 s40, s40, 14
	global_load_lds_dwordx4 v227, s[94:95]
	global_load_lds_dwordx4 v227, s[94:95] offset:1024
	s_add_u32 s94, s92, s40
	s_addc_u32 s95, s93, 0
	s_add_u32 m0, m0, 0x2000
	s_nop 0
	global_load_lds_dwordx4 v227, s[94:95]
	global_load_lds_dwordx4 v227, s[94:95] offset:1024
	s_mov_b32 s7, 12
	s_mov_b32 s9, 6
	s_lshl_b32 s94, s9, 14
	s_add_u32 s94, s94, s8
	s_mov_b32 m0, s94
	s_add_i32 s40, s59, s7
	s_and_b32 s40, s40, 62
	s_lshl_b32 s94, s40, 12
	s_add_u32 s94, vcc_lo, s94
	s_addc_u32 s95, vcc_hi, 0
	s_lshl_b32 s40, s40, 14
	global_load_lds_dwordx4 v227, s[94:95]
	global_load_lds_dwordx4 v227, s[94:95] offset:1024
	s_add_u32 s94, s92, s40
	s_addc_u32 s95, s93, 0
	s_add_u32 m0, m0, 0x2000
	s_nop 0
	global_load_lds_dwordx4 v227, s[94:95]
	global_load_lds_dwordx4 v227, s[94:95] offset:1024
	s_mov_b32 s7, 14
	s_mov_b32 s9, 7
	s_lshl_b32 s94, s9, 14
	s_add_u32 s94, s94, s8
	s_mov_b32 m0, s94
	s_add_i32 s40, s59, s7
	s_and_b32 s40, s40, 62
	s_lshl_b32 s94, s40, 12
	s_add_u32 s94, vcc_lo, s94
	s_addc_u32 s95, vcc_hi, 0
	s_lshl_b32 s40, s40, 14
	global_load_lds_dwordx4 v227, s[94:95]
	global_load_lds_dwordx4 v227, s[94:95] offset:1024
	s_add_u32 s94, s92, s40
	s_addc_u32 s95, s93, 0
	s_add_u32 m0, m0, 0x2000
	s_nop 0
	global_load_lds_dwordx4 v227, s[94:95]
	global_load_lds_dwordx4 v227, s[94:95] offset:1024
	s_mov_b32 s7, 16
	s_mov_b32 s9, 0
	s_mov_b32 s10, 1
	s_waitcnt vmcnt(26)
	s_barrier
	v_add_u32_e32 v225, v38, v40
	v_add_u32_e32 v224, v38, v39
	ds_read_b128 v[54:57], v224
	ds_read_b128 v[58:61], v224 offset:1024
	ds_read_b128 v[62:65], v224 offset:2048
	ds_read_b128 v[46:49], v225 offset:8192
	ds_read_b128 v[50:53], v225 offset:9216
	ds_read_b128 v[216:219], v224 offset:3072
; DI f32x4 mfma16(bf16x8 a, bf16x8 b, f32x4 c) { return __builtin_amdgcn_mfma_f32_16x16x32_bf16(a, b, c, 0, 0, 0); }
; template <int N> DI void wait_vm() { asm volatile("s_waitcnt vmcnt(%0)" ::"n"(N) : "memory"); }
; DI void raw_barrier() { asm volatile("" ::: "memory"); __builtin_amdgcn_s_barrier(); asm volatile("" ::: "memory"); }
;     ...
;     auto compute = [&](int cb, bool do_issue, int ikt, int ib) {
;         const char* base = lds + cb * BUF;
;         bf16x8 af[MT], bfr[NT];
; #pragma unroll
;         for (int nt = 0; nt < NT; ++nt) {
;             const int br = BM + (nt / NTS) * (BN / NSEG) + wc * (NTS * 16) + (nt % NTS) * 16;
;             bfr[nt] = *(const bf16x8*)(base + (br + l15) * 64 + rsw);
;         }
; #pragma unroll
;         for (int mt = 0; mt < MT; ++mt) af[mt] = *(const bf16x8*)(base + (wr * WM + mt * 16 + l15) * 64 + rsw);
;         constexpr int TOT = MT * NT, PER = (TOT + NIT - 1) / NIT;
; #pragma unroll
;         for (int part = 0; part < NIT; ++part) {
; #pragma unroll
;             for (int q = 0; q < PER; ++q) {
;                 const int idx = part * PER + q;
;                 if (idx < TOT) {
;                     const int mt = idx / NT, nt = idx % NT;
;                     acc[mt][nt] = SWAP ? mfma16(bfr[nt], af[mt], acc[mt][nt]) : mfma16(af[mt], bfr[nt], acc[mt][nt]);
;                 }
;             }
;             __builtin_amdgcn_sched_barrier(0);
;             if (do_issue) issue_one(ikt, ib, part);
;             __builtin_amdgcn_sched_barrier(0);
;         }
;     };
;     __syncthreads();
; #pragma unroll
;     for (int d = 0; d < D; ++d) issue(d, d);
;     int cb = 0, ib = D;
;     for (int kt = 0; kt < KT; ++kt) {
;         if (D > 1 && kt + D - 1 < KT) wait_vm<(D - 1) * NIT>(); else wait_vm<0>();
;         raw_barrier();
;         compute(cb, kt + D < KT, kt + D, ib);
;         cb = (cb + 1 == NST) ? 0 : cb + 1;
;         ib = (ib + 1 == NST) ? 0 : ib + 1;
;     }
.Lpkv_l_loop:
	s_lshl_b32 s94, s10, 14
	v_add_u32_e32 v226, s94, v38
	v_add_u32_e32 v225, v226, v40
	v_add_u32_e32 v224, v226, v39
	s_waitcnt lgkmcnt(2)
	v_mfma_f32_16x16x32_bf16 v[30:33], v[46:49], v[54:57], v[30:33]
	s_waitcnt lgkmcnt(1)
	v_mfma_f32_16x16x32_bf16 v[26:29], v[50:53], v[54:57], v[26:29]
	s_waitcnt vmcnt(24) lgkmcnt(0)
	s_barrier
	ds_read_b128 v[54:57], v224
	s_lshl_b32 s94, s9, 14
	s_add_u32 s94, s94, s8
	s_mov_b32 m0, s94
	s_add_i32 s40, s59, s7
	s_and_b32 s40, s40, 62
	s_lshl_b32 s94, s40, 12
	s_add_u32 s94, vcc_lo, s94
	s_addc_u32 s95, vcc_hi, 0
	s_lshl_b32 s40, s40, 14
	global_load_lds_dwordx4 v227, s[94:95]
	global_load_lds_dwordx4 v227, s[94:95] offset:1024
	v_mfma_f32_16x16x32_bf16 v[22:25], v[46:49], v[58:61], v[22:25]
	v_mfma_f32_16x16x32_bf16 v[18:21], v[50:53], v[58:61], v[18:21]
	s_add_u32 s94, s92, s40
	s_addc_u32 s95, s93, 0
	s_add_u32 m0, m0, 0x2000
	s_nop 0
	global_load_lds_dwordx4 v227, s[94:95]
	global_load_lds_dwordx4 v227, s[94:95] offset:1024
	ds_read_b128 v[58:61], v224 offset:1024
	v_mfma_f32_16x16x32_bf16 v[14:17], v[46:49], v[62:65], v[14:17]
	v_mfma_f32_16x16x32_bf16 v[10:13], v[50:53], v[62:65], v[10:13]
	ds_read_b128 v[62:65], v224 offset:2048
	v_mfma_f32_16x16x32_bf16 v[6:9], v[46:49], v[216:219], v[6:9]
	ds_read_b128 v[46:49], v225 offset:8192
	v_mfma_f32_16x16x32_bf16 v[2:5], v[50:53], v[216:219], v[2:5]
	ds_read_b128 v[50:53], v225 offset:9216
	ds_read_b128 v[216:219], v224 offset:3072
	s_add_i32 s10, s10, 1
	s_cmp_lg_u32 s10, 8
	s_cselect_b32 s10, s10, 0
	s_add_i32 s9, s9, 1
	s_cmp_lg_u32 s9, 8
	s_cselect_b32 s9, s9, 0
	s_add_i32 s7, s7, 2
	s_cmp_lg_u32 s7, 64
	s_cbranch_scc1 .Lpkv_l_loop
	s_lshl_b32 s94, s10, 14
	v_add_u32_e32 v226, s94, v38
	v_add_u32_e32 v225, v226, v40
	v_add_u32_e32 v224, v226, v39
	s_waitcnt lgkmcnt(2)
	v_mfma_f32_16x16x32_bf16 v[30:33], v[46:49], v[54:57], v[30:33]
	s_waitcnt lgkmcnt(1)
	v_mfma_f32_16x16x32_bf16 v[26:29], v[50:53], v[54:57], v[26:29]
	s_waitcnt vmcnt(24) lgkmcnt(0)
	s_barrier
	ds_read_b128 v[54:57], v224
	v_mfma_f32_16x16x32_bf16 v[22:25], v[46:49], v[58:61], v[22:25]
	v_mfma_f32_16x16x32_bf16 v[18:21], v[50:53], v[58:61], v[18:21]
	ds_read_b128 v[58:61], v224 offset:1024
	v_mfma_f32_16x16x32_bf16 v[14:17], v[46:49], v[62:65], v[14:17]
	v_mfma_f32_16x16x32_bf16 v[10:13], v[50:53], v[62:65], v[10:13]
	ds_read_b128 v[62:65], v224 offset:2048
	v_mfma_f32_16x16x32_bf16 v[6:9], v[46:49], v[216:219], v[6:9]
	ds_read_b128 v[46:49], v225 offset:8192
	v_mfma_f32_16x16x32_bf16 v[2:5], v[50:53], v[216:219], v[2:5]
	ds_read_b128 v[50:53], v225 offset:9216
	ds_read_b128 v[216:219], v224 offset:3072
	s_add_i32 s10, s10, 1
	s_cmp_lg_u32 s10, 8
	s_cselect_b32 s10, s10, 0
	s_lshl_b32 s94, s10, 14
	v_add_u32_e32 v226, s94, v38
	v_add_u32_e32 v225, v226, v40
	v_add_u32_e32 v224, v226, v39
	s_waitcnt lgkmcnt(2)
	v_mfma_f32_16x16x32_bf16 v[30:33], v[46:49], v[54:57], v[30:33]
	s_waitcnt lgkmcnt(1)
	v_mfma_f32_16x16x32_bf16 v[26:29], v[50:53], v[54:57], v[26:29]
	s_waitcnt vmcnt(20) lgkmcnt(0)
	s_barrier
	ds_read_b128 v[54:57], v224
	v_mfma_f32_16x16x32_bf16 v[22:25], v[46:49], v[58:61], v[22:25]
	v_mfma_f32_16x16x32_bf16 v[18:21], v[50:53], v[58:61], v[18:21]
	ds_read_b128 v[58:61], v224 offset:1024
	v_mfma_f32_16x16x32_bf16 v[14:17], v[46:49], v[62:65], v[14:17]
	v_mfma_f32_16x16x32_bf16 v[10:13], v[50:53], v[62:65], v[10:13]
	ds_read_b128 v[62:65], v224 offset:2048
	v_mfma_f32_16x16x32_bf16 v[6:9], v[46:49], v[216:219], v[6:9]
	ds_read_b128 v[46:49], v225 offset:8192
	v_mfma_f32_16x16x32_bf16 v[2:5], v[50:53], v[216:219], v[2:5]
	ds_read_b128 v[50:53], v225 offset:9216
	ds_read_b128 v[216:219], v224 offset:3072
	s_add_i32 s10, s10, 1
	s_cmp_lg_u32 s10, 8
	s_cselect_b32 s10, s10, 0
	s_lshl_b32 s94, s10, 14
	v_add_u32_e32 v226, s94, v38
	v_add_u32_e32 v225, v226, v40
	v_add_u32_e32 v224, v226, v39
	s_waitcnt lgkmcnt(2)
	v_mfma_f32_16x16x32_bf16 v[30:33], v[46:49], v[54:57], v[30:33]
	s_waitcnt lgkmcnt(1)
	v_mfma_f32_16x16x32_bf16 v[26:29], v[50:53], v[54:57], v[26:29]
	s_waitcnt vmcnt(16) lgkmcnt(0)
	s_barrier
	ds_read_b128 v[54:57], v224
	v_mfma_f32_16x16x32_bf16 v[22:25], v[46:49], v[58:61], v[22:25]
	v_mfma_f32_16x16x32_bf16 v[18:21], v[50:53], v[58:61], v[18:21]
	ds_read_b128 v[58:61], v224 offset:1024
	v_mfma_f32_16x16x32_bf16 v[14:17], v[46:49], v[62:65], v[14:17]
	v_mfma_f32_16x16x32_bf16 v[10:13], v[50:53], v[62:65], v[10:13]
	ds_read_b128 v[62:65], v224 offset:2048
	v_mfma_f32_16x16x32_bf16 v[6:9], v[46:49], v[216:219], v[6:9]
	ds_read_b128 v[46:49], v225 offset:8192
	v_mfma_f32_16x16x32_bf16 v[2:5], v[50:53], v[216:219], v[2:5]
	ds_read_b128 v[50:53], v225 offset:9216
	ds_read_b128 v[216:219], v224 offset:3072
	s_add_i32 s10, s10, 1
	s_cmp_lg_u32 s10, 8
	s_cselect_b32 s10, s10, 0
	s_lshl_b32 s94, s10, 14
	v_add_u32_e32 v226, s94, v38
	v_add_u32_e32 v225, v226, v40
	v_add_u32_e32 v224, v226, v39
	s_waitcnt lgkmcnt(2)
	v_mfma_f32_16x16x32_bf16 v[30:33], v[46:49], v[54:57], v[30:33]
	s_waitcnt lgkmcnt(1)
	v_mfma_f32_16x16x32_bf16 v[26:29], v[50:53], v[54:57], v[26:29]
	s_waitcnt vmcnt(12) lgkmcnt(0)
	s_barrier
	ds_read_b128 v[54:57], v224
	v_mfma_f32_16x16x32_bf16 v[22:25], v[46:49], v[58:61], v[22:25]
	v_mfma_f32_16x16x32_bf16 v[18:21], v[50:53], v[58:61], v[18:21]
	ds_read_b128 v[58:61], v224 offset:1024
	v_mfma_f32_16x16x32_bf16 v[14:17], v[46:49], v[62:65], v[14:17]
	v_mfma_f32_16x16x32_bf16 v[10:13], v[50:53], v[62:65], v[10:13]
	ds_read_b128 v[62:65], v224 offset:2048
	v_mfma_f32_16x16x32_bf16 v[6:9], v[46:49], v[216:219], v[6:9]
	ds_read_b128 v[46:49], v225 offset:8192
	v_mfma_f32_16x16x32_bf16 v[2:5], v[50:53], v[216:219], v[2:5]
	ds_read_b128 v[50:53], v225 offset:9216
	ds_read_b128 v[216:219], v224 offset:3072
	s_add_i32 s10, s10, 1
	s_cmp_lg_u32 s10, 8
	s_cselect_b32 s10, s10, 0
	s_lshl_b32 s94, s10, 14
	v_add_u32_e32 v226, s94, v38
	v_add_u32_e32 v225, v226, v40
	v_add_u32_e32 v224, v226, v39
	s_waitcnt lgkmcnt(2)
	v_mfma_f32_16x16x32_bf16 v[30:33], v[46:49], v[54:57], v[30:33]
	s_waitcnt lgkmcnt(1)
	v_mfma_f32_16x16x32_bf16 v[26:29], v[50:53], v[54:57], v[26:29]
	s_waitcnt vmcnt(8) lgkmcnt(0)
	s_barrier
; DI f32x4 mfma16(bf16x8 a, bf16x8 b, f32x4 c) { return __builtin_amdgcn_mfma_f32_16x16x32_bf16(a, b, c, 0, 0, 0); }
; template <int N> DI void wait_vm() { asm volatile("s_waitcnt vmcnt(%0)" ::"n"(N) : "memory"); }
; DI void raw_barrier() { asm volatile("" ::: "memory"); __builtin_amdgcn_s_barrier(); asm volatile("" ::: "memory"); }
;     ...
;     auto compute = [&](int cb, bool do_issue, int ikt, int ib) {
;         const char* base = lds + cb * BUF;
;         bf16x8 af[MT], bfr[NT];
; #pragma unroll
;         for (int nt = 0; nt < NT; ++nt) {
;             const int br = BM + (nt / NTS) * (BN / NSEG) + wc * (NTS * 16) + (nt % NTS) * 16;
;             bfr[nt] = *(const bf16x8*)(base + (br + l15) * 64 + rsw);
;         }
; #pragma unroll
;         for (int mt = 0; mt < MT; ++mt) af[mt] = *(const bf16x8*)(base + (wr * WM + mt * 16 + l15) * 64 + rsw);
;         constexpr int TOT = MT * NT, PER = (TOT + NIT - 1) / NIT;
; #pragma unroll
;         for (int part = 0; part < NIT; ++part) {
; #pragma unroll
;             for (int q = 0; q < PER; ++q) {
;                 const int idx = part * PER + q;
;                 if (idx < TOT) {
;                     const int mt = idx / NT, nt = idx % NT;
;                     acc[mt][nt] = SWAP ? mfma16(bfr[nt], af[mt], acc[mt][nt]) : mfma16(af[mt], bfr[nt], acc[mt][nt]);
;                 }
;             }
;             __builtin_amdgcn_sched_barrier(0);
;             if (do_issue) issue_one(ikt, ib, part);
;             __builtin_amdgcn_sched_barrier(0);
;         }
;     };
;     __syncthreads();
; #pragma unroll
;     for (int d = 0; d < D; ++d) issue(d, d);
;     int cb = 0, ib = D;
;     for (int kt = 0; kt < KT; ++kt) {
;         if (D > 1 && kt + D - 1 < KT) wait_vm<(D - 1) * NIT>(); else wait_vm<0>();
;         raw_barrier();
;         compute(cb, kt + D < KT, kt + D, ib);
;         cb = (cb + 1 == NST) ? 0 : cb + 1;
;         ib = (ib + 1 == NST) ? 0 : ib + 1;
;     }
	ds_read_b128 v[54:57], v224
	v_mfma_f32_16x16x32_bf16 v[22:25], v[46:49], v[58:61], v[22:25]
	v_mfma_f32_16x16x32_bf16 v[18:21], v[50:53], v[58:61], v[18:21]
	ds_read_b128 v[58:61], v224 offset:1024
	v_mfma_f32_16x16x32_bf16 v[14:17], v[46:49], v[62:65], v[14:17]
	v_mfma_f32_16x16x32_bf16 v[10:13], v[50:53], v[62:65], v[10:13]
	ds_read_b128 v[62:65], v224 offset:2048
	v_mfma_f32_16x16x32_bf16 v[6:9], v[46:49], v[216:219], v[6:9]
	ds_read_b128 v[46:49], v225 offset:8192
	v_mfma_f32_16x16x32_bf16 v[2:5], v[50:53], v[216:219], v[2:5]
	ds_read_b128 v[50:53], v225 offset:9216
	ds_read_b128 v[216:219], v224 offset:3072
	s_add_i32 s10, s10, 1
	s_cmp_lg_u32 s10, 8
	s_cselect_b32 s10, s10, 0
	s_lshl_b32 s94, s10, 14
	v_add_u32_e32 v226, s94, v38
	v_add_u32_e32 v225, v226, v40
	v_add_u32_e32 v224, v226, v39
	s_waitcnt lgkmcnt(2)
	v_mfma_f32_16x16x32_bf16 v[30:33], v[46:49], v[54:57], v[30:33]
	s_waitcnt lgkmcnt(1)
	v_mfma_f32_16x16x32_bf16 v[26:29], v[50:53], v[54:57], v[26:29]
	s_waitcnt vmcnt(4) lgkmcnt(0)
	s_barrier
	ds_read_b128 v[54:57], v224
	v_mfma_f32_16x16x32_bf16 v[22:25], v[46:49], v[58:61], v[22:25]
	v_mfma_f32_16x16x32_bf16 v[18:21], v[50:53], v[58:61], v[18:21]
	ds_read_b128 v[58:61], v224 offset:1024
	v_mfma_f32_16x16x32_bf16 v[14:17], v[46:49], v[62:65], v[14:17]
	v_mfma_f32_16x16x32_bf16 v[10:13], v[50:53], v[62:65], v[10:13]
	ds_read_b128 v[62:65], v224 offset:2048
	v_mfma_f32_16x16x32_bf16 v[6:9], v[46:49], v[216:219], v[6:9]
	ds_read_b128 v[46:49], v225 offset:8192
	v_mfma_f32_16x16x32_bf16 v[2:5], v[50:53], v[216:219], v[2:5]
	ds_read_b128 v[50:53], v225 offset:9216
	ds_read_b128 v[216:219], v224 offset:3072
	s_add_i32 s10, s10, 1
	s_cmp_lg_u32 s10, 8
	s_cselect_b32 s10, s10, 0
	s_lshl_b32 s94, s10, 14
	v_add_u32_e32 v226, s94, v38
	v_add_u32_e32 v225, v226, v40
	v_add_u32_e32 v224, v226, v39
	s_waitcnt lgkmcnt(2)
	v_mfma_f32_16x16x32_bf16 v[30:33], v[46:49], v[54:57], v[30:33]
	s_waitcnt lgkmcnt(1)
	v_mfma_f32_16x16x32_bf16 v[26:29], v[50:53], v[54:57], v[26:29]
	s_waitcnt vmcnt(0) lgkmcnt(0)
	s_barrier
	ds_read_b128 v[54:57], v224
	v_mfma_f32_16x16x32_bf16 v[22:25], v[46:49], v[58:61], v[22:25]
	v_mfma_f32_16x16x32_bf16 v[18:21], v[50:53], v[58:61], v[18:21]
	ds_read_b128 v[58:61], v224 offset:1024
	v_mfma_f32_16x16x32_bf16 v[14:17], v[46:49], v[62:65], v[14:17]
	v_mfma_f32_16x16x32_bf16 v[10:13], v[50:53], v[62:65], v[10:13]
	ds_read_b128 v[62:65], v224 offset:2048
	v_mfma_f32_16x16x32_bf16 v[6:9], v[46:49], v[216:219], v[6:9]
	ds_read_b128 v[46:49], v225 offset:8192
	v_mfma_f32_16x16x32_bf16 v[2:5], v[50:53], v[216:219], v[2:5]
	ds_read_b128 v[50:53], v225 offset:9216
	ds_read_b128 v[216:219], v224 offset:3072
	s_add_i32 s10, s10, 1
	s_cmp_lg_u32 s10, 8
	s_cselect_b32 s10, s10, 0
	s_waitcnt lgkmcnt(2)
	v_mfma_f32_16x16x32_bf16 v[30:33], v[46:49], v[54:57], v[30:33]
	s_waitcnt lgkmcnt(1)
	v_mfma_f32_16x16x32_bf16 v[26:29], v[50:53], v[54:57], v[26:29]
	s_waitcnt lgkmcnt(0)
	v_mfma_f32_16x16x32_bf16 v[22:25], v[46:49], v[58:61], v[22:25]
	v_mfma_f32_16x16x32_bf16 v[18:21], v[50:53], v[58:61], v[18:21]
	v_mfma_f32_16x16x32_bf16 v[14:17], v[46:49], v[62:65], v[14:17]
	v_mfma_f32_16x16x32_bf16 v[10:13], v[50:53], v[62:65], v[10:13]
	v_mfma_f32_16x16x32_bf16 v[6:9], v[46:49], v[216:219], v[6:9]
	v_mfma_f32_16x16x32_bf16 v[2:5], v[50:53], v[216:219], v[2:5]
	s_branch .Lpkv_join
.Lpkv_c_entry:
	s_mov_b32 s7, 16
	s_mov_b32 s10, 1
	s_waitcnt vmcnt(2)
	s_barrier
	v_add_u32_e32 v225, v38, v40
	v_add_u32_e32 v224, v38, v39
	ds_read_b128 v[54:57], v224
	ds_read_b128 v[58:61], v224 offset:1024
	ds_read_b128 v[62:65], v224 offset:2048
	ds_read_b128 v[46:49], v225 offset:8192
	ds_read_b128 v[50:53], v225 offset:9216
	ds_read_b128 v[216:219], v224 offset:3072
.Lpkv_c_loop:
	s_lshl_b32 s94, s10, 14
	v_add_u32_e32 v226, s94, v38
	v_add_u32_e32 v225, v226, v40
	v_add_u32_e32 v224, v226, v39
	s_waitcnt lgkmcnt(2)
	v_mfma_f32_16x16x32_bf16 v[30:33], v[46:49], v[54:57], v[30:33]
	s_waitcnt lgkmcnt(1)
	v_mfma_f32_16x16x32_bf16 v[26:29], v[50:53], v[54:57], v[26:29]
	s_waitcnt vmcnt(0) lgkmcnt(0)
	s_barrier
	ds_read_b128 v[54:57], v224
	v_mfma_f32_16x16x32_bf16 v[22:25], v[46:49], v[58:61], v[22:25]
	v_mfma_f32_16x16x32_bf16 v[18:21], v[50:53], v[58:61], v[18:21]
	ds_read_b128 v[58:61], v224 offset:1024
	v_mfma_f32_16x16x32_bf16 v[14:17], v[46:49], v[62:65], v[14:17]
	v_mfma_f32_16x16x32_bf16 v[10:13], v[50:53], v[62:65], v[10:13]
	ds_read_b128 v[62:65], v224 offset:2048
	v_mfma_f32_16x16x32_bf16 v[6:9], v[46:49], v[216:219], v[6:9]
	ds_read_b128 v[46:49], v225 offset:8192
	v_mfma_f32_16x16x32_bf16 v[2:5], v[50:53], v[216:219], v[2:5]
	ds_read_b128 v[50:53], v225 offset:9216
	ds_read_b128 v[216:219], v224 offset:3072
	s_add_i32 s10, s10, 1
	s_cmp_lg_u32 s10, 8
	s_cselect_b32 s10, s10, 0
	s_add_i32 s7, s7, 2
	s_cmp_lg_u32 s7, 64
	s_cbranch_scc1 .Lpkv_c_loop
	s_lshl_b32 s94, s10, 14
	v_add_u32_e32 v226, s94, v38
	v_add_u32_e32 v225, v226, v40
	v_add_u32_e32 v224, v226, v39
	s_waitcnt lgkmcnt(2)
	v_mfma_f32_16x16x32_bf16 v[30:33], v[46:49], v[54:57], v[30:33]
	s_waitcnt lgkmcnt(1)
	v_mfma_f32_16x16x32_bf16 v[26:29], v[50:53], v[54:57], v[26:29]
	s_waitcnt vmcnt(0) lgkmcnt(0)
	s_barrier
; DI f32x4 mfma16(bf16x8 a, bf16x8 b, f32x4 c) { return __builtin_amdgcn_mfma_f32_16x16x32_bf16(a, b, c, 0, 0, 0); }
; template <int N> DI void wait_vm() { asm volatile("s_waitcnt vmcnt(%0)" ::"n"(N) : "memory"); }
; DI void raw_barrier() { asm volatile("" ::: "memory"); __builtin_amdgcn_s_barrier(); asm volatile("" ::: "memory"); }
;     ...
;     auto compute = [&](int cb, bool do_issue, int ikt, int ib) {
;         const char* base = lds + cb * BUF;
;         bf16x8 af[MT], bfr[NT];
; #pragma unroll
;         for (int nt = 0; nt < NT; ++nt) {
;             const int br = BM + (nt / NTS) * (BN / NSEG) + wc * (NTS * 16) + (nt % NTS) * 16;
;             bfr[nt] = *(const bf16x8*)(base + (br + l15) * 64 + rsw);
;         }
; #pragma unroll
;         for (int mt = 0; mt < MT; ++mt) af[mt] = *(const bf16x8*)(base + (wr * WM + mt * 16 + l15) * 64 + rsw);
;         constexpr int TOT = MT * NT, PER = (TOT + NIT - 1) / NIT;
; #pragma unroll
;         for (int part = 0; part < NIT; ++part) {
; #pragma unroll
;             for (int q = 0; q < PER; ++q) {
;                 const int idx = part * PER + q;
;                 if (idx < TOT) {
;                     const int mt = idx / NT, nt = idx % NT;
;                     acc[mt][nt] = SWAP ? mfma16(bfr[nt], af[mt], acc[mt][nt]) : mfma16(af[mt], bfr[nt], acc[mt][nt]);
;                 }
;             }
;             __builtin_amdgcn_sched_barrier(0);
;             if (do_issue) issue_one(ikt, ib, part);
;             __builtin_amdgcn_sched_barrier(0);
;         }
;     };
;     __syncthreads();
; #pragma unroll
;     for (int d = 0; d < D; ++d) issue(d, d);
;     int cb = 0, ib = D;
;     for (int kt = 0; kt < KT; ++kt) {
;         if (D > 1 && kt + D - 1 < KT) wait_vm<(D - 1) * NIT>(); else wait_vm<0>();
;         raw_barrier();
;         compute(cb, kt + D < KT, kt + D, ib);
;         cb = (cb + 1 == NST) ? 0 : cb + 1;
;         ib = (ib + 1 == NST) ? 0 : ib + 1;
	ds_read_b128 v[54:57], v224
	v_mfma_f32_16x16x32_bf16 v[22:25], v[46:49], v[58:61], v[22:25]
	v_mfma_f32_16x16x32_bf16 v[18:21], v[50:53], v[58:61], v[18:21]
	ds_read_b128 v[58:61], v224 offset:1024
	v_mfma_f32_16x16x32_bf16 v[14:17], v[46:49], v[62:65], v[14:17]
	v_mfma_f32_16x16x32_bf16 v[10:13], v[50:53], v[62:65], v[10:13]
	ds_read_b128 v[62:65], v224 offset:2048
	v_mfma_f32_16x16x32_bf16 v[6:9], v[46:49], v[216:219], v[6:9]
	ds_read_b128 v[46:49], v225 offset:8192
	v_mfma_f32_16x16x32_bf16 v[2:5], v[50:53], v[216:219], v[2:5]
	ds_read_b128 v[50:53], v225 offset:9216
	ds_read_b128 v[216:219], v224 offset:3072
	s_add_i32 s10, s10, 1
	s_cmp_lg_u32 s10, 8
	s_cselect_b32 s10, s10, 0
	s_lshl_b32 s94, s10, 14
	v_add_u32_e32 v226, s94, v38
	v_add_u32_e32 v225, v226, v40
	v_add_u32_e32 v224, v226, v39
	s_waitcnt lgkmcnt(2)
	v_mfma_f32_16x16x32_bf16 v[30:33], v[46:49], v[54:57], v[30:33]
	s_waitcnt lgkmcnt(1)
	v_mfma_f32_16x16x32_bf16 v[26:29], v[50:53], v[54:57], v[26:29]
	s_waitcnt vmcnt(0) lgkmcnt(0)
	s_barrier
	ds_read_b128 v[54:57], v224
	v_mfma_f32_16x16x32_bf16 v[22:25], v[46:49], v[58:61], v[22:25]
	v_mfma_f32_16x16x32_bf16 v[18:21], v[50:53], v[58:61], v[18:21]
	ds_read_b128 v[58:61], v224 offset:1024
	v_mfma_f32_16x16x32_bf16 v[14:17], v[46:49], v[62:65], v[14:17]
	v_mfma_f32_16x16x32_bf16 v[10:13], v[50:53], v[62:65], v[10:13]
	ds_read_b128 v[62:65], v224 offset:2048
	v_mfma_f32_16x16x32_bf16 v[6:9], v[46:49], v[216:219], v[6:9]
	ds_read_b128 v[46:49], v225 offset:8192
	v_mfma_f32_16x16x32_bf16 v[2:5], v[50:53], v[216:219], v[2:5]
	ds_read_b128 v[50:53], v225 offset:9216
	ds_read_b128 v[216:219], v224 offset:3072
	s_add_i32 s10, s10, 1
	s_cmp_lg_u32 s10, 8
	s_cselect_b32 s10, s10, 0
	s_lshl_b32 s94, s10, 14
	v_add_u32_e32 v226, s94, v38
	v_add_u32_e32 v225, v226, v40
	v_add_u32_e32 v224, v226, v39
	s_waitcnt lgkmcnt(2)
	v_mfma_f32_16x16x32_bf16 v[30:33], v[46:49], v[54:57], v[30:33]
	s_waitcnt lgkmcnt(1)
	v_mfma_f32_16x16x32_bf16 v[26:29], v[50:53], v[54:57], v[26:29]
	s_waitcnt vmcnt(0) lgkmcnt(0)
	s_barrier
	ds_read_b128 v[54:57], v224
	v_mfma_f32_16x16x32_bf16 v[22:25], v[46:49], v[58:61], v[22:25]
	v_mfma_f32_16x16x32_bf16 v[18:21], v[50:53], v[58:61], v[18:21]
	ds_read_b128 v[58:61], v224 offset:1024
	v_mfma_f32_16x16x32_bf16 v[14:17], v[46:49], v[62:65], v[14:17]
	v_mfma_f32_16x16x32_bf16 v[10:13], v[50:53], v[62:65], v[10:13]
	ds_read_b128 v[62:65], v224 offset:2048
	v_mfma_f32_16x16x32_bf16 v[6:9], v[46:49], v[216:219], v[6:9]
	ds_read_b128 v[46:49], v225 offset:8192
	v_mfma_f32_16x16x32_bf16 v[2:5], v[50:53], v[216:219], v[2:5]
	ds_read_b128 v[50:53], v225 offset:9216
	ds_read_b128 v[216:219], v224 offset:3072
	s_add_i32 s10, s10, 1
	s_cmp_lg_u32 s10, 8
	s_cselect_b32 s10, s10, 0
	s_lshl_b32 s94, s10, 14
	v_add_u32_e32 v226, s94, v38
	v_add_u32_e32 v225, v226, v40
	v_add_u32_e32 v224, v226, v39
	s_waitcnt lgkmcnt(2)
	v_mfma_f32_16x16x32_bf16 v[30:33], v[46:49], v[54:57], v[30:33]
	s_waitcnt lgkmcnt(1)
	v_mfma_f32_16x16x32_bf16 v[26:29], v[50:53], v[54:57], v[26:29]
	s_waitcnt vmcnt(0) lgkmcnt(0)
	s_barrier
	ds_read_b128 v[54:57], v224
	v_mfma_f32_16x16x32_bf16 v[22:25], v[46:49], v[58:61], v[22:25]
	v_mfma_f32_16x16x32_bf16 v[18:21], v[50:53], v[58:61], v[18:21]
	ds_read_b128 v[58:61], v224 offset:1024
	v_mfma_f32_16x16x32_bf16 v[14:17], v[46:49], v[62:65], v[14:17]
	v_mfma_f32_16x16x32_bf16 v[10:13], v[50:53], v[62:65], v[10:13]
	ds_read_b128 v[62:65], v224 offset:2048
	v_mfma_f32_16x16x32_bf16 v[6:9], v[46:49], v[216:219], v[6:9]
	ds_read_b128 v[46:49], v225 offset:8192
	v_mfma_f32_16x16x32_bf16 v[2:5], v[50:53], v[216:219], v[2:5]
	ds_read_b128 v[50:53], v225 offset:9216
	ds_read_b128 v[216:219], v224 offset:3072
	s_add_i32 s10, s10, 1
	s_cmp_lg_u32 s10, 8
	s_cselect_b32 s10, s10, 0
	s_lshl_b32 s94, s10, 14
	v_add_u32_e32 v226, s94, v38
	v_add_u32_e32 v225, v226, v40
	v_add_u32_e32 v224, v226, v39
	s_waitcnt lgkmcnt(2)
	v_mfma_f32_16x16x32_bf16 v[30:33], v[46:49], v[54:57], v[30:33]
	s_waitcnt lgkmcnt(1)
	v_mfma_f32_16x16x32_bf16 v[26:29], v[50:53], v[54:57], v[26:29]
	s_waitcnt vmcnt(0) lgkmcnt(0)
	s_barrier
	ds_read_b128 v[54:57], v224
	v_mfma_f32_16x16x32_bf16 v[22:25], v[46:49], v[58:61], v[22:25]
	v_mfma_f32_16x16x32_bf16 v[18:21], v[50:53], v[58:61], v[18:21]
	ds_read_b128 v[58:61], v224 offset:1024
	v_mfma_f32_16x16x32_bf16 v[14:17], v[46:49], v[62:65], v[14:17]
	v_mfma_f32_16x16x32_bf16 v[10:13], v[50:53], v[62:65], v[10:13]
	ds_read_b128 v[62:65], v224 offset:2048
	v_mfma_f32_16x16x32_bf16 v[6:9], v[46:49], v[216:219], v[6:9]
	ds_read_b128 v[46:49], v225 offset:8192
	v_mfma_f32_16x16x32_bf16 v[2:5], v[50:53], v[216:219], v[2:5]
	ds_read_b128 v[50:53], v225 offset:9216
	ds_read_b128 v[216:219], v224 offset:3072
	s_add_i32 s10, s10, 1
	s_cmp_lg_u32 s10, 8
	s_cselect_b32 s10, s10, 0
	s_lshl_b32 s94, s10, 14
	v_add_u32_e32 v226, s94, v38
	v_add_u32_e32 v225, v226, v40
	v_add_u32_e32 v224, v226, v39
	s_waitcnt lgkmcnt(2)
	v_mfma_f32_16x16x32_bf16 v[30:33], v[46:49], v[54:57], v[30:33]
	s_waitcnt lgkmcnt(1)
	v_mfma_f32_16x16x32_bf16 v[26:29], v[50:53], v[54:57], v[26:29]
	s_waitcnt vmcnt(0) lgkmcnt(0)
	s_barrier
;     ...
;     auto compute = [&](int cb, bool do_issue, int ikt, int ib) {
;         const char* base = lds + cb * BUF;
;         bf16x8 af[MT], bfr[NT];
; #pragma unroll
;         for (int nt = 0; nt < NT; ++nt) {
;             const int br = BM + (nt / NTS) * (BN / NSEG) + wc * (NTS * 16) + (nt % NTS) * 16;
;             bfr[nt] = *(const bf16x8*)(base + (br + l15) * 64 + rsw);
;         }
; #pragma unroll
;         for (int mt = 0; mt < MT; ++mt) af[mt] = *(const bf16x8*)(base + (wr * WM + mt * 16 + l15) * 64 + rsw);
;         constexpr int TOT = MT * NT, PER = (TOT + NIT - 1) / NIT;
; #pragma unroll
;         for (int part = 0; part < NIT; ++part) {
; #pragma unroll
;             for (int q = 0; q < PER; ++q) {
;                 const int idx = part * PER + q;
;                 if (idx < TOT) {
;                     const int mt = idx / NT, nt = idx % NT;
;                     acc[mt][nt] = SWAP ? mfma16(bfr[nt], af[mt], acc[mt][nt]) : mfma16(af[mt], bfr[nt], acc[mt][nt]);
;                 }
;             }
;             __builtin_amdgcn_sched_barrier(0);
;             if (do_issue) issue_one(ikt, ib, part);
;             __builtin_amdgcn_sched_barrier(0);
;         }
;     };
;     __syncthreads();
; #pragma unroll
;     for (int d = 0; d < D; ++d) issue(d, d);
;     int cb = 0, ib = D;
;     for (int kt = 0; kt < KT; ++kt) {
;         if (D > 1 && kt + D - 1 < KT) wait_vm<(D - 1) * NIT>(); else wait_vm<0>();
;         raw_barrier();
;         compute(cb, kt + D < KT, kt + D, ib);
;         cb = (cb + 1 == NST) ? 0 : cb + 1;
;         ib = (ib + 1 == NST) ? 0 : ib + 1;
;     }
;     __syncthreads();
; DI void unit_KV(const Params& p, char* lds, int l, int mtile, int q) {
;     ...
;         const int r = mtile * 128 + wr * 64 + mt * 16 + l15, b = r >> 8, m = r & 255;
; #pragma unroll
;         for (int nt = 0; nt < 2; ++nt) {
;             const int col = 128 * q + wc * 32 + nt * 16 + quad * 4;
;             const f32x4 v = acc[mt][nt];
;             if (q < 2) {
;                 const int head = col >> 6, d = col & 63;
;                 *(u32x2*)(Kb + ((size_t)((b * 4 + head) * 256 + m)) * 64 + d) = (u32x2){pk2(v[0], v[1]), pk2(v[2], v[3])};
;             } else {
;                 const int cv = col - 256, head = cv >> 6, d = cv & 63;
;                 const int rr = m & 31, pos = (m & ~31) + 8 * ((rr >> 2) & 3) + 4 * (rr >> 4) + (rr & 3);
; #pragma unroll
	ds_read_b128 v[54:57], v224
	v_mfma_f32_16x16x32_bf16 v[22:25], v[46:49], v[58:61], v[22:25]
	v_mfma_f32_16x16x32_bf16 v[18:21], v[50:53], v[58:61], v[18:21]
	ds_read_b128 v[58:61], v224 offset:1024
	v_mfma_f32_16x16x32_bf16 v[14:17], v[46:49], v[62:65], v[14:17]
	v_mfma_f32_16x16x32_bf16 v[10:13], v[50:53], v[62:65], v[10:13]
	ds_read_b128 v[62:65], v224 offset:2048
	v_mfma_f32_16x16x32_bf16 v[6:9], v[46:49], v[216:219], v[6:9]
	ds_read_b128 v[46:49], v225 offset:8192
	v_mfma_f32_16x16x32_bf16 v[2:5], v[50:53], v[216:219], v[2:5]
	ds_read_b128 v[50:53], v225 offset:9216
	ds_read_b128 v[216:219], v224 offset:3072
	s_add_i32 s10, s10, 1
	s_cmp_lg_u32 s10, 8
	s_cselect_b32 s10, s10, 0
	s_lshl_b32 s94, s10, 14
	v_add_u32_e32 v226, s94, v38
	v_add_u32_e32 v225, v226, v40
	v_add_u32_e32 v224, v226, v39
	s_waitcnt lgkmcnt(2)
	v_mfma_f32_16x16x32_bf16 v[30:33], v[46:49], v[54:57], v[30:33]
	s_waitcnt lgkmcnt(1)
	v_mfma_f32_16x16x32_bf16 v[26:29], v[50:53], v[54:57], v[26:29]
	s_waitcnt vmcnt(0) lgkmcnt(0)
	s_barrier
	ds_read_b128 v[54:57], v224
	v_mfma_f32_16x16x32_bf16 v[22:25], v[46:49], v[58:61], v[22:25]
	v_mfma_f32_16x16x32_bf16 v[18:21], v[50:53], v[58:61], v[18:21]
	ds_read_b128 v[58:61], v224 offset:1024
	v_mfma_f32_16x16x32_bf16 v[14:17], v[46:49], v[62:65], v[14:17]
	v_mfma_f32_16x16x32_bf16 v[10:13], v[50:53], v[62:65], v[10:13]
	ds_read_b128 v[62:65], v224 offset:2048
	v_mfma_f32_16x16x32_bf16 v[6:9], v[46:49], v[216:219], v[6:9]
	ds_read_b128 v[46:49], v225 offset:8192
	v_mfma_f32_16x16x32_bf16 v[2:5], v[50:53], v[216:219], v[2:5]
	ds_read_b128 v[50:53], v225 offset:9216
	ds_read_b128 v[216:219], v224 offset:3072
	s_add_i32 s10, s10, 1
	s_cmp_lg_u32 s10, 8
	s_cselect_b32 s10, s10, 0
	s_waitcnt lgkmcnt(2)
	v_mfma_f32_16x16x32_bf16 v[30:33], v[46:49], v[54:57], v[30:33]
	s_waitcnt lgkmcnt(1)
	v_mfma_f32_16x16x32_bf16 v[26:29], v[50:53], v[54:57], v[26:29]
	s_waitcnt lgkmcnt(0)
	v_mfma_f32_16x16x32_bf16 v[22:25], v[46:49], v[58:61], v[22:25]
	v_mfma_f32_16x16x32_bf16 v[18:21], v[50:53], v[58:61], v[18:21]
	v_mfma_f32_16x16x32_bf16 v[14:17], v[46:49], v[62:65], v[14:17]
	v_mfma_f32_16x16x32_bf16 v[10:13], v[50:53], v[62:65], v[10:13]
	v_mfma_f32_16x16x32_bf16 v[6:9], v[46:49], v[216:219], v[6:9]
	v_mfma_f32_16x16x32_bf16 v[2:5], v[50:53], v[216:219], v[2:5]
.Lpkv_join:
	s_lshl_b32 s14, s3, 7
	s_lshl_b32 s6, s6, 1
	v_readlane_b32 s7, v243, 12
	s_add_u32 s8, s7, s6
	v_readlane_b32 s7, v243, 13
	s_addc_u32 s9, s7, 0
	v_readlane_b32 s7, v243, 14
	v_ashrrev_i32_e32 v0, 2, v44
	s_add_u32 s10, s7, s6
	v_readlane_b32 s6, v243, 15
	v_and_b32_e32 v0, 0xffffffc0, v0
	s_addc_u32 s11, s6, 0
	v_lshl_add_u32 v34, s0, 7, v0
	v_lshrrev_b32_e32 v36, 1, v44
	v_lshrrev_b32_e32 v0, 2, v44
	v_and_b32_e32 v35, 0x60, v36
	v_and_b32_e32 v37, 12, v0
	s_cmp_gt_u32 s3, 1
	v_mov_b32_e32 v0, s14
	s_movk_i32 s3, 0x1c0
	v_lshlrev_b32_e32 v38, 1, v44
	v_and_b32_e32 v39, 3, v44
	v_and_b32_e32 v54, 0xc0, v34
	v_bitop3_b32 v0, v35, s3, v0 bitop3:0xc8
	v_and_or_b32 v55, v38, 24, v39
	v_and_b32_e32 v38, 0xffffff00, v34
	s_movk_i32 s3, 0xff00
	v_add3_u32 v45, v0, v38, s3
	v_or_b32_e32 v0, v54, v55
	v_lshlrev_b32_e32 v0, 1, v0
	v_lshl_add_u64 v[50:51], s[10:11], 0, v[0:1]
	v_and_or_b32 v0, v36, 32, v37
	s_cselect_b64 s[12:13], -1, 0
	v_or_b32_e32 v42, v45, v0
	s_mov_b64 s[6:7], -1
	s_and_b64 vcc, exec, s[12:13]
	v_ashrrev_i32_e32 v43, 31, v42
	v_or_b32_e32 v40, 1, v42
	v_or_b32_e32 v38, 2, v42
	v_or_b32_e32 v36, 3, v42
	s_waitcnt vmcnt(0)
	s_barrier
	s_cbranch_vccz .LBB0_864
	v_lshlrev_b64 v[46:47], 9, v[42:43]
	v_cvt_pk_bf16_f32 v37, v30, s0
	v_lshl_add_u64 v[46:47], v[50:51], 0, v[46:47]
	v_ashrrev_i32_e32 v41, 31, v40
	global_store_short v[46:47], v37, off
	v_lshlrev_b64 v[46:47], 9, v[40:41]
	v_cvt_pk_bf16_f32 v37, v31, s0
	v_lshl_add_u64 v[46:47], v[50:51], 0, v[46:47]
	v_ashrrev_i32_e32 v39, 31, v38
	global_store_short v[46:47], v37, off
	v_lshlrev_b64 v[46:47], 9, v[38:39]
	v_cvt_pk_bf16_f32 v37, v32, s0
	v_lshl_add_u64 v[46:47], v[50:51], 0, v[46:47]
	global_store_short v[46:47], v37, off
	v_ashrrev_i32_e32 v37, 31, v36
	v_lshlrev_b64 v[46:47], 9, v[36:37]
	v_cvt_pk_bf16_f32 v39, v33, s0
	v_lshl_add_u64 v[46:47], v[50:51], 0, v[46:47]
	global_store_short v[46:47], v39, off
	s_mov_b64 s[6:7], 0
